# phase-start table loads overlapped (post, stage3) and in-proj row-scale table finished after the first operand loads are issued
# baseline (speedup 1.0000x reference)
; #define LAS __attribute__((address_space(3)))
; __device__ __forceinline__ float frsq(float x) { return __builtin_amdgcn_rsqf(x); }
; __global__ void __launch_bounds__(512) hymba_fwd(Args a) {
;     ...
;             if (G == 256) {
;                 pg8::Unit u0; if (S.next(0, u0) && threadIdx.x < 256) { const float* rss = (const float*)(a.ws + WS_RSS) + u0.pm * 256 + threadIdx.x;
;                     ((LAS float*)(lds + 131072))[threadIdx.x] = frsq(((rss[0] + rss[NTOK]) + (rss[2 * NTOK] + rss[3 * NTOK])) * (1.f / 1024.f) + EPS); }
;                 __syncthreads();
.LBB0_249:
	s_and_b64 vcc, exec, s[14:15]
	s_cbranch_vccz .LBB0_331
	v_readlane_b32 s4, v246, 8
	v_readlane_b32 s5, v246, 9
	s_andn2_b64 vcc, exec, s[4:5]
	s_nop 0
	v_cndmask_b32_e64 v0, 0, 1, s[4:5]
	v_cmp_ne_u32_e64 s[40:41], 1, v0
	s_mov_b64 s[14:15], exec
	v_readlane_b32 s4, v246, 10
	v_readlane_b32 s5, v246, 11
	s_and_b64 s[4:5], s[14:15], s[4:5]
	s_mov_b64 exec, s[4:5]
	s_cbranch_execz .LBB0_252
	v_readlane_b32 s4, v244, 35
	s_lshl_b32 s4, s4, 8
	s_ashr_i32 s5, s4, 31
	v_lshl_add_u64 v[0:1], s[4:5], 2, v[146:147]
	v_add_co_u32_e32 v4, vcc, 0x10000, v0
	global_load_dword v242, v[0:1], off
	s_nop 0
	v_addc_co_u32_e32 v5, vcc, 0, v1, vcc
	v_add_co_u32_e32 v6, vcc, 0x20000, v0
	global_load_dword v243, v[4:5], off
	s_nop 0
	v_addc_co_u32_e32 v7, vcc, 0, v1, vcc
	v_add_co_u32_e32 v0, vcc, 0x30000, v0
	global_load_dword v247, v[6:7], off
	s_nop 0
	v_addc_co_u32_e32 v1, vcc, 0, v1, vcc
	global_load_dword v165, v[0:1], off

; #define LAS __attribute__((address_space(3)))
; __device__ __forceinline__ float frsq(float x) { return __builtin_amdgcn_rsqf(x); }
; #define PG8_STAGE(bufoff, gbase, voff) do { _Pragma("unroll") for (int _i = 0; _i < 2; ++_i) \
;         __builtin_amdgcn_global_load_lds((const unsigned*)((const char*)(gbase) + (voff)[_i]), (LAS unsigned*)(lds + (bufoff) + ldsw + _i * 8192), 16, 0, 0); } while (0)
; #define PG8_WAIT_V(n) asm volatile("s_waitcnt vmcnt(" #n ")" ::: "memory")
; #define PG8_BAR __builtin_amdgcn_s_barrier()
; template <class Epi, class Sched>
; __device__ __forceinline__ void gemm_phase(LAS unsigned char* lds, const Gemm g, const Sched& S, const Epi& E) {
;     ...
;     PG8_STAGE(PG8_SB(0, 0), cB, voffB); PG8_STAGE(PG8_SB(0, 1), cB + hstepB, voffB); PG8_STAGE(PG8_SA(0, 0), cA, voffA); PG8_STAGE(PG8_SA(0, 1), cA + hstepA, voffA);
;     if (wr == 1) PG8_BAR;
;     PG8_WAIT_V(2); PG8_BAR;
;     PG8_STAGE(PG8_SB(1, 0), cB + kstep, voffB); PG8_STAGE(PG8_SA(1, 0), cA + kstep, voffA); PG8_STAGE(PG8_SB(1, 1), cB + hstepB + kstep, voffB);
;     PG8_WAIT_V(6); PG8_BAR;
; __global__ void __launch_bounds__(512) hymba_fwd(Args a) {
;     ...
;                 pg8::Unit u0; if (S.next(0, u0) && threadIdx.x < 256) { const float* rss = (const float*)(a.ws + WS_RSS) + u0.pm * 256 + threadIdx.x;
;                     ((LAS float*)(lds + 131072))[threadIdx.x] = frsq(((rss[0] + rss[NTOK]) + (rss[2 * NTOK] + rss[3 * NTOK])) * (1.f / 1024.f) + EPS); }
.LBB0_255:
	v_and_b32_e32 v160, 15, v10
	v_lshrrev_b32_e32 v10, 1, v10
	v_readlane_b32 s18, v244, 31
	v_and_b32_e32 v161, 24, v10
	s_lshl_b32 s16, s16, 5
	v_mov_b32_e32 v135, v145
	v_readlane_b32 s19, v244, 32
	v_lshlrev_b32_e32 v10, 1, v161
	v_lshlrev_b32_e32 v11, 2, v160
	s_and_b32 s36, s16, 0x60
	s_add_i32 m0, s8, 0x18000
	v_lshl_add_u64 v[0:1], v[0:1], 0, s[0:1]
	v_lshl_add_u64 v[12:13], s[18:19], 0, v[134:135]
	v_mov_b32_e32 v131, v145
	s_lshl_b32 s35, s5, 6
	v_lshl_or_b32 v10, v160, 6, v10
	s_lshl_b32 s17, s5, 13
	v_and_b32_e32 v16, 32, v11
	s_lshl_b32 s16, s36, 7
	s_waitcnt vmcnt(2)
	s_barrier
	global_load_lds_dwordx4 v[0:1], off
	v_lshl_add_u64 v[0:1], v[2:3], 0, s[0:1]
	s_add_i32 m0, s8, 0x1a000
	s_add_i32 s37, s8, 0x8000
	s_add_i32 s38, s8, 0xa000
	v_lshl_add_u64 v[14:15], s[18:19], 0, v[130:131]
	v_bitop3_b32 v162, v10, s16, v16 bitop3:0xde
	global_load_lds_dwordx4 v[0:1], off
	v_lshl_add_u64 v[0:1], v[12:13], 0, s[0:1]
	s_mov_b32 m0, s37
	s_add_u32 s16, s14, 0x40080
	v_bitop3_b32 v17, v10, s17, v16 bitop3:0xde
	global_load_lds_dwordx4 v[0:1], off
	v_lshl_add_u64 v[0:1], v[14:15], 0, s[0:1]
	s_mov_b32 m0, s38
	s_addc_u32 s17, s15, 0
	global_load_lds_dwordx4 v[0:1], off
	s_add_i32 m0, s8, 0x1c000
	v_lshl_add_u64 v[0:1], s[16:17], 0, v[132:133]
	global_load_lds_dwordx4 v[0:1], off
	v_lshl_add_u64 v[0:1], s[16:17], 0, v[128:129]
	s_add_i32 m0, s8, 0x1e000
	s_cmpk_lt_u32 s4, 0x100
	global_load_lds_dwordx4 v[0:1], off
	v_lshlrev_b32_e32 v0, 14, v8
	v_and_b32_e32 v0, 0xffff8000, v0
	v_lshl_add_u32 v0, v7, 11, v0
	v_and_b32_e32 v1, 1, v8
	v_lshl_or_b32 v0, v1, 6, v0
	v_lshl_add_u32 v136, v9, 1, v0
	v_lshlrev_b32_e32 v0, 14, v4
	s_cselect_b64 s[50:51], -1, 0
	s_lshl_b32 s4, s5, 8
	v_and_b32_e32 v0, 0xffff8000, v0
	s_waitcnt vmcnt(6)
	s_mov_b64 s[98:99], exec
	v_readlane_b32 s100, v246, 10
	v_readlane_b32 s101, v246, 11
	s_and_b64 s[100:101], s[98:99], s[100:101]
	s_mov_b64 exec, s[100:101]
	v_add_f32_e32 v242, v242, v243
	v_add_f32_e32 v247, v247, v165
	s_nop 0
	v_add_f32_e32 v242, v242, v247
	s_nop 0
	v_fmamk_f32 v242, v242, 0x3a800000, v186
	s_nop 0
	v_rsq_f32_e32 v242, v242
	s_nop 1
	ds_write_b32 v184, v242
	s_mov_b64 exec, s[98:99]
	s_add_i32 s4, s4, 0
	v_lshl_add_u32 v0, v5, 11, v0
	v_and_b32_e32 v1, 1, v4
	v_readlane_b32 s16, v244, 27
	s_add_i32 s4, s4, 0x20000
	v_lshl_or_b32 v0, v1, 6, v0
	v_readlane_b32 s17, v244, 28
	v_add_u32_e32 v163, s4, v11
	v_mov_b32_e32 v137, v145
	v_lshl_add_u32 v138, v6, 1, v0
	v_mov_b32_e32 v139, v145
	s_mov_b32 s4, 0
	v_add_u32_e32 v164, 0, v17
	v_readlane_b32 s39, v244, 10
	s_mov_b32 s5, s16
	s_mov_b64 s[16:17], s[18:19]
	s_barrier
	s_waitcnt vmcnt(0)
	s_branch .LBB0_258

; #define LAS __attribute__((address_space(3)))
; __global__ void __launch_bounds__(512) hymba_fwd(Args a) {
;     ...
;                 if (tid < 128) ((LAS float*)(lds + 68608))[tid] = (tid < 64) ? a.mqn[l * 64 + tid] : a.mkn[l * 64 + tid - 64];
;                 if (tid < 512) ((LAS float*)(lds + 106496))[tid] = ((const float*)(a.ws + WS_LB))[l * 512 + tid];
.LBB0_419:
	v_readlane_b32 s4, v245, 28
	v_readlane_b32 s5, v245, 29
	s_andn2_b64 vcc, exec, s[4:5]
	s_waitcnt vmcnt(0)
	s_barrier
	s_cbranch_vccnz .LBB0_449
	v_mov_b32_e32 v96, v178
	s_movk_i32 s4, 0x7f
	s_nop 0
	v_cmp_lt_i32_e64 s[42:43], s4, v96
	s_movk_i32 s4, 0x80
	v_cmp_gt_i32_e32 vcc, s4, v96
	v_lshl_add_u32 v101, v96, 2, 0
	s_and_saveexec_b64 s[14:15], vcc
	s_cbranch_execz .LBB0_422
	v_readlane_b32 s4, v244, 61
	v_cmp_gt_i32_e32 vcc, 64, v96
	s_nop 0
	v_lshl_add_u32 v0, s4, 6, v96
	v_ashrrev_i32_e32 v1, 31, v0
	v_lshl_add_u64 v[2:3], v[0:1], 2, s[92:93]
	v_mov_b32_e32 v1, v145
	s_movk_i32 s4, 0xff00
	v_lshl_add_u64 v[0:1], v[0:1], 2, s[94:95]
	s_mov_b32 s5, -1
	v_lshl_add_u64 v[0:1], v[0:1], 0, s[4:5]
	v_cndmask_b32_e32 v1, v1, v3, vcc
	v_cndmask_b32_e32 v0, v0, v2, vcc
	global_load_dword v240, v[0:1], off
	v_add_u32_e32 v241, 0x10c00, v101

; #define LAS __attribute__((address_space(3)))
; __global__ void __launch_bounds__(512) hymba_fwd(Args a) {
;     ...
;                 if (tid < 128) ((LAS float*)(lds + 68608))[tid] = (tid < 64) ? a.mqn[l * 64 + tid] : a.mkn[l * 64 + tid - 64];
;                 if (tid < 512) ((LAS float*)(lds + 106496))[tid] = ((const float*)(a.ws + WS_LB))[l * 512 + tid];
;                 __syncthreads();
;                 { PrepIn cur; int u = wb; moba_prep_load(a, tid, u < 512 ? u : 0, cur);
;                   for (; u < 512; u += WG) { PrepIn nxt; moba_prep_unit(a, l, lds, tid, u, cur, nxt, (u + WG < 512) ? u + WG : u); cur = nxt; } }
.LBB0_424:
	s_or_b64 exec, exec, s[14:15]
	s_movk_i32 s4, 0x80
	v_cmp_gt_i32_e32 vcc, s4, v96
	s_and_saveexec_b64 s[14:15], vcc
	ds_write_b32 v241, v240
	s_or_b64 exec, exec, s[14:15]
	v_readlane_b32 s4, v245, 32
	v_readlane_b32 s5, v245, 33
	s_andn2_b64 vcc, exec, s[4:5]
	v_lshlrev_b32_e32 v124, 5, v96
	v_ashrrev_i32_e32 v97, 31, v96
	s_waitcnt lgkmcnt(0)
	s_barrier
	s_cbranch_vccnz .LBB0_435
	v_ashrrev_i32_e32 v98, 1, v96
	v_lshlrev_b32_e32 v196, 6, v96
	v_add_u32_e32 v196, 0x11000, v196
	v_and_b32_e32 v199, 63, v96
	v_lshrrev_b32_e32 v198, 6, v96
	v_lshlrev_b32_e32 v197, 4, v199
	v_lshl_or_b32 v197, v198, 12, v197
	v_add_u32_e32 v197, 0x11000, v197
	v_lshrrev_b32_e32 v201, 3, v199
	v_and_b32_e32 v200, 7, v199
	v_lshlrev_b32_e32 v200, 4, v200
	v_lshl_or_b32 v200, v201, 13, v200
	v_lshlrev_b32_e32 v199, 4, v199
	v_add_u32_e32 v201, 0x10000, v200
	v_add_u32_e32 v202, 0x20000, v200
	v_add_u32_e32 v203, 0x30000, v200
	v_readlane_b32 s4, v244, 8
	v_ashrrev_i32_e32 v99, 31, v98
	v_readlane_b32 s5, v244, 9
	v_and_b32_e32 v0, 32, v124
	v_lshlrev_b32_e32 v144, 1, v0
	v_lshl_add_u64 v[2:3], v[98:99], 0, s[4:5]
	v_readlane_b32 s4, v245, 34
	v_readlane_b32 s5, v245, 35
	v_and_b32_e32 v1, 1, v96
	v_lshlrev_b32_e32 v100, 5, v1
	v_lshl_add_u64 v[4:5], v[2:3], 0, s[4:5]
	v_readlane_b32 s4, v245, 40
	v_lshlrev_b64 v[6:7], 6, v[4:5]
	v_readlane_b32 s5, v245, 41
	v_lshlrev_b64 v[2:3], 7, v[2:3]
	v_cmp_eq_u32_e64 s[44:45], 0, v1
	v_lshl_add_u64 v[6:7], s[4:5], 0, v[6:7]
	v_readlane_b32 s4, v245, 38
	v_readlane_b32 s5, v245, 39
	global_load_dwordx4 v[48:51], v[6:7], off offset:48
	global_load_dwordx4 v[52:55], v[6:7], off offset:16
	global_load_dwordx4 v[56:59], v[6:7], off
	global_load_dwordx4 v[60:63], v[6:7], off offset:32
	v_lshl_add_u64 v[2:3], s[4:5], 0, v[2:3]
	v_lshl_add_u64 v[2:3], v[2:3], 0, v[144:145]
	v_readlane_b32 s4, v245, 36
	global_load_dwordx4 v[64:67], v[2:3], off offset:48
	global_load_dwordx4 v[68:71], v[2:3], off offset:32
	global_load_dwordx4 v[72:75], v[2:3], off offset:16
	global_load_dwordx4 v[76:79], v[2:3], off
	v_lshlrev_b64 v[2:3], 13, v[4:5]
	v_readlane_b32 s5, v245, 37
	v_lshrrev_b32_e32 v4, 5, v98
	v_cmp_gt_i32_e64 s[46:47], 64, v96
	v_lshl_add_u64 v[2:3], s[4:5], 0, v[2:3]
	v_lshl_add_u64 v[2:3], v[2:3], 0, v[144:145]
	global_load_dwordx4 v[80:83], v[2:3], off offset:48
	global_load_dwordx4 v[84:87], v[2:3], off offset:32
	global_load_dwordx4 v[88:91], v[2:3], off offset:16
	global_load_dwordx4 v[92:95], v[2:3], off
	s_add_i32 s4, 0, 0x10c00
	v_lshlrev_b32_e32 v2, 7, v1
	v_add_u32_e32 v125, s4, v2
	s_movk_i32 s4, 0x104
	v_add_u32_e32 v1, 0, v2
	v_mul_lo_u32 v2, v98, s4
	v_readlane_b32 s4, v244, 50
	v_and_b32_e32 v3, 63, v96
	v_lshlrev_b32_e32 v3, 2, v3
	v_lshl_add_u32 v126, v96, 2, s4
	s_movk_i32 s4, 0x2080
	v_mul_lo_u32 v4, v4, s4
	v_add3_u32 v127, v4, v3, 0
	v_lshlrev_b32_e32 v102, 1, v0
	v_add_u32_e32 v128, v1, v2
	v_readlane_b32 s5, v245, 44
	s_waitcnt vmcnt(11)
	v_mov_b32_e32 v105, v51
	s_waitcnt vmcnt(10)
	v_mov_b32_e32 v104, v55
	s_branch .LBB0_427

; #define LAS __attribute__((address_space(3)))
; __device__ __forceinline__ int otid() { int t = threadIdx.x; asm volatile("" : "+v"(t)); return t; }
; __global__ void __launch_bounds__(512) hymba_fwd(Args a) {
;     ...
;             { const int tid = otid();
;               if (tid < 512) ((LAS float*)(lds + 106496))[tid] = ((const float*)(a.ws + WS_LB))[l * 512 + tid];
;               if (tid < 128) ((LAS float*)(lds + 106496 + 2048))[tid] = a.hon[l * 128 + tid];
.LBB0_636:
	s_andn2_b64 vcc, exec, s[14:15]
	s_cbranch_vccnz .LBB0_742
	s_waitcnt vmcnt(1)
	v_mov_b32_e32 v121, v178
	s_movk_i32 s4, 0x200
	s_nop 0
	v_cmp_gt_i32_e32 vcc, s4, v121
	v_lshl_add_u32 v123, v121, 2, 0
	s_and_saveexec_b64 s[14:15], vcc
	s_cbranch_execz .LBB0_639
	v_readlane_b32 s4, v244, 61
	v_add_u32_e32 v241, 0x1a000, v123
	s_nop 0
	v_lshl_add_u32 v0, s4, 9, v121
	v_readlane_b32 s4, v245, 30
	v_ashrrev_i32_e32 v1, 31, v0
	v_readlane_b32 s5, v245, 31
	s_nop 1
	v_lshl_add_u64 v[0:1], v[0:1], 2, s[4:5]
	global_load_dword v240, v[0:1], off

; #define LAS __attribute__((address_space(3)))
; __device__ __forceinline__ int otid() { int t = threadIdx.x; asm volatile("" : "+v"(t)); return t; }
; __device__ __forceinline__ void hgrn_stage3_unit(const Args& a, int l, LAS unsigned char* lds, int tid, int u, const HIn& in, HIn& nxt, int unext) {
;     const int lane = tid & 63, w = __builtin_amdgcn_readfirstlane(tid >> 6), fr = lane & 15, fq = lane >> 4;
;     const int bh = u >> 5, c = u & 31, b = bh >> 2, hh = bh & 3; const size_t row0 = (size_t)b * SEQ + c * 64;
;     const int tt = w & 3, vh = w >> 2;
;     bf16_t* proj = (bf16_t*)(a.ws + WS_PROJ);
;     LAS float* LF = (LAS float*)lds;
;     LAS unsigned char* QM = lds + 34816;
;     LAS unsigned char* Q0 = QM + 17408;
;     LAS unsigned char* KM = Q0 + 17408;
;     LAS unsigned char* VN = KM + 17408;
;     LAS float* SSQ = (LAS float*)(VN + 18432);
;     float kf[16];
;     hgrn_stepA(a, l, lds, tid, hh, in, kf);
;     const size_t row = row0 + tt * 16 + fr;
;     const bf16_t* ST = (const bf16_t*)(a.ws + WS_H) + ((size_t)bh * 32 + c) * 16384;
;     bf16x8 stf[4][4]; u32x2 zz[4];
; #pragma unroll
;     for (int ks = 0; ks < 4; ++ks)
; #pragma unroll
;         for (int v = 0; v < 4; ++v) stf[ks][v] = *(const bf16x8*)(ST + ((vh * 4 + v) * 16 + fr) * 128 + ks * 32 + fq * 8);
; #pragma unroll
;     for (int v = 0; v < 4; ++v) zz[v] = *(const u32x2*)(proj + row * NCOL + CZ + 512 + hh * 128 + (vh * 4 + v) * 16 + fq * 4);
;     hgrn_load<true>(a, tid, unext, nxt);
;     hgrn_cumsum_scan(lds, tid);
; __global__ void __launch_bounds__(512) hymba_fwd(Args a) {
;     ...
;             { const int tid = otid();
;               if (tid < 512) ((LAS float*)(lds + 106496))[tid] = ((const float*)(a.ws + WS_LB))[l * 512 + tid];
;               if (tid < 128) ((LAS float*)(lds + 106496 + 2048))[tid] = a.hon[l * 128 + tid];
;               __syncthreads();
;               HIn cur; int u = bx; hgrn_load<true>(a, tid, u < 1024 ? u : 0, cur);
;                 for (; u < 1024; u += G) { HIn nxt; hgrn_stage3_unit(a, l, lds, tid, u, cur, nxt, (u + G < 1024) ? u + G : u); cur = nxt; } }
.LBB0_641:
	s_or_b64 exec, exec, s[14:15]
	s_waitcnt vmcnt(0)
	ds_write_b32 v241, v240
	v_readlane_b32 s4, v245, 56
	v_readlane_b32 s5, v245, 57
	s_andn2_b64 vcc, exec, s[4:5]
	s_waitcnt lgkmcnt(0)
	s_barrier
	s_cbranch_vccnz .LBB0_680
	v_add_u32_e32 v0, 0x200, v121
	v_ashrrev_i32_e32 v118, 4, v0
	v_readlane_b32 s4, v245, 58
	v_ashrrev_i32_e32 v119, 31, v118
	v_readlane_b32 s5, v245, 59
	v_lshlrev_b32_e32 v9, 3, v121
	v_ashrrev_i32_e32 v116, 4, v121
	v_lshl_add_u64 v[0:1], s[4:5], 0, v[118:119]
	v_readlane_b32 s8, v245, 60
	v_and_b32_e32 v8, 0x78, v9
	v_ashrrev_i32_e32 v117, 31, v116
	v_lshlrev_b64 v[0:1], 13, v[0:1]
	v_readlane_b32 s9, v245, 61
	v_lshlrev_b32_e32 v144, 1, v8
	v_lshl_add_u64 v[6:7], s[4:5], 0, v[116:117]
	v_lshl_add_u64 v[0:1], s[8:9], 0, v[0:1]
	v_lshl_add_u64 v[0:1], v[0:1], 0, v[144:145]
	v_lshlrev_b64 v[6:7], 13, v[6:7]
	v_add_co_u32_e32 v4, vcc, s26, v0
	v_lshl_add_u64 v[6:7], s[8:9], 0, v[6:7]
	s_nop 0
	v_addc_co_u32_e32 v5, vcc, 0, v1, vcc
	v_lshl_add_u64 v[6:7], v[6:7], 0, v[144:145]
	global_load_dwordx4 v[28:31], v[0:1], off offset:1024
	s_nop 0
	global_load_dwordx4 v[0:3], v[4:5], off offset:2048
	global_load_dwordx4 v[24:27], v[4:5], off offset:3072
	global_load_dwordx4 v[100:103], v[6:7], off offset:1024
	v_add_co_u32_e32 v4, vcc, s26, v6
	v_bfe_u32 v11, v121, 4, 2
	s_nop 0
	v_addc_co_u32_e32 v5, vcc, 0, v7, vcc
	global_load_dwordx4 v[72:75], v[4:5], off offset:3072
	s_nop 0
	global_load_dwordx4 v[4:7], v[4:5], off offset:2048
	v_lshlrev_b32_e32 v122, 2, v11
	s_add_i32 s4, 0, 0x1a000
	v_lshlrev_b32_e32 v10, 2, v8
	v_and_b32_e32 v120, 15, v121
	v_or_b32_e32 v32, 2, v122
	v_add_u32_e32 v170, s4, v10
	v_add_u32_e32 v171, 0, v10
	v_lshlrev_b32_e32 v10, 5, v121
	v_and_b32_e32 v12, 0x7f, v121
	v_readlane_b32 s4, v244, 53
	v_cmp_gt_u32_e64 s[52:53], v32, v120
	v_or_b32_e32 v32, 3, v122
	v_and_b32_e32 v10, 0xfffffe00, v10
	v_ashrrev_i32_e32 v13, 7, v121
	v_lshl_add_u32 v174, v12, 2, 0
	v_readlane_b32 s5, v244, 54
	v_lshlrev_b32_e32 v17, 4, v11
	v_mov_b32_e32 v21, s4
	v_cmp_gt_u32_e64 s[54:55], v32, v120
	v_bfe_u32 v32, v121, 2, 2
	v_add_u32_e32 v172, v171, v10
	v_lshlrev_b32_e32 v10, 3, v11
	v_lshl_add_u32 v175, v13, 13, v174
	v_cmp_lt_i32_e64 s[42:43], 0, v13
	v_cmp_lt_i32_e64 s[44:45], 1, v13
	v_cmp_lt_i32_e64 s[46:47], 2, v13
	v_add_u32_e32 v177, s4, v144
	v_add_u32_e32 v12, s5, v144
	v_lshlrev_b32_e32 v13, 9, v116
	v_mul_lo_u32 v14, v116, s27
	v_lshlrev_b32_e32 v15, 9, v118
	v_mul_lo_u32 v16, v118, s27
	v_add_u32_e32 v18, s4, v17
	v_mul_u32_u24_e32 v19, 0x110, v120
	v_or_b32_e32 v20, 64, v17
	v_mad_u32_u24 v21, v120, s31, v21
	v_or_b32_e32 v22, 0x80, v17
	v_or_b32_e32 v23, 0xc0, v17
	v_and_b32_e32 v182, 24, v9
	v_or_b32_e32 v9, v122, v32
	v_mov_b32_e32 v32, s5
	v_readlane_b32 s4, v244, 55
	v_lshlrev_b32_e32 v173, 7, v120
	v_sub_u32_e32 v176, v171, v144
	v_mul_lo_u32 v180, v116, s31
	v_mul_lo_u32 v181, v118, s31
	v_cmp_gt_u32_e64 s[48:49], v122, v120
	v_cmp_ge_u32_e64 s[50:51], v122, v120
	v_mad_u32_u24 v183, v9, s27, v32
	v_add_u32_e32 v195, 0, v17
	v_cmp_eq_u32_e64 s[56:57], 0, v11
	v_lshl_add_u32 v196, v120, 2, s4
	v_lshlrev_b32_e32 v144, 1, v10
	v_lshlrev_b32_e32 v124, 1, v8
	v_add_u32_e32 v197, v171, v13
	v_add_u32_e32 v198, v12, v14
	v_add_u32_e32 v199, v171, v15
	v_add_u32_e32 v200, v12, v16
	v_add_u32_e32 v201, v18, v19
	v_add_u32_e32 v202, v21, v20
	v_add_u32_e32 v203, v21, v22
	v_add_u32_e32 v204, v21, v23
	s_mov_b32 s8, s2
	s_branch .LBB0_644
